# combo8 + GEMM ping-pong: loading half runs at priority 2 (computing half stays at 1)
# baseline (speedup 1.0000x reference)
.LBB0_290:
	s_add_u32 s26, s24, 0xfffc0080
	s_addc_u32 s27, s25, -1
	s_add_u32 s52, s24, 0xfffc0000
	s_addc_u32 s53, s25, -1
	s_mov_b32 m0, s43
	ds_read_b128 v[130:133], v188
	ds_read_b128 v[134:137], v188 offset:1024
	ds_read_b128 v[138:141], v188 offset:2048
	ds_read_b128 v[154:157], v188 offset:3072
	ds_read_b128 v[158:161], v188 offset:16384
	ds_read_b128 v[162:165], v188 offset:17408
	ds_read_b128 v[166:169], v188 offset:18432
	ds_read_b128 v[176:179], v188 offset:19456
	ds_read_b128 v[180:183], v175
	ds_read_b128 v[184:187], v175 offset:1024
	ds_read_b128 v[192:195], v175 offset:2048
	ds_read_b128 v[196:199], v175 offset:3072
	ds_read_b128 v[200:203], v175 offset:4096
	ds_read_b128 v[204:207], v175 offset:5120
	ds_read_b128 v[208:211], v175 offset:6144
	ds_read_b128 v[212:215], v175 offset:7168
	global_load_lds_dwordx4 v144, s[52:53]
	s_add_i32 m0, s38, 0xc000
	s_nop 0
	global_load_lds_dwordx4 v150, s[24:25]
	s_add_i32 m0, s38, 0xe000
	s_cmp_eq_u32 s50, 12
	global_load_lds_dwordx4 v152, s[24:25]
	s_cselect_b32 s29, s17, s27
	s_cselect_b32 s28, s46, s26
	s_cselect_b32 s27, s15, s49
	s_cselect_b32 s26, s47, s48
	s_waitcnt vmcnt(8)
	s_waitcnt lgkmcnt(0)
	s_barrier
	s_setprio 1
	s_waitcnt lgkmcnt(0)
	v_mfma_f32_16x16x32_bf16 v[126:129], v[130:133], v[180:183], v[126:129]
	v_mfma_f32_16x16x32_bf16 v[122:125], v[138:141], v[180:183], v[122:125]
	v_mfma_f32_16x16x32_bf16 v[110:113], v[130:133], v[192:195], v[110:113]
	v_mfma_f32_16x16x32_bf16 v[106:109], v[138:141], v[192:195], v[106:109]
	v_mfma_f32_16x16x32_bf16 v[94:97], v[130:133], v[200:203], v[94:97]
	v_mfma_f32_16x16x32_bf16 v[90:93], v[138:141], v[200:203], v[90:93]
	v_mfma_f32_16x16x32_bf16 v[78:81], v[130:133], v[208:211], v[78:81]
	v_mfma_f32_16x16x32_bf16 v[74:77], v[138:141], v[208:211], v[74:77]
	v_mfma_f32_16x16x32_bf16 v[126:129], v[134:137], v[184:187], v[126:129]
	v_mfma_f32_16x16x32_bf16 v[122:125], v[154:157], v[184:187], v[122:125]
	v_mfma_f32_16x16x32_bf16 v[110:113], v[134:137], v[196:199], v[110:113]
	v_mfma_f32_16x16x32_bf16 v[106:109], v[154:157], v[196:199], v[106:109]
	v_mfma_f32_16x16x32_bf16 v[94:97], v[134:137], v[204:207], v[94:97]
	v_mfma_f32_16x16x32_bf16 v[90:93], v[154:157], v[204:207], v[90:93]
	v_mfma_f32_16x16x32_bf16 v[78:81], v[134:137], v[212:215], v[78:81]
	v_mfma_f32_16x16x32_bf16 v[74:77], v[154:157], v[212:215], v[74:77]
	s_setprio 0
	s_setprio 1
	v_mfma_f32_16x16x32_bf16 v[118:121], v[158:161], v[180:183], v[118:121]
	v_mfma_f32_16x16x32_bf16 v[114:117], v[166:169], v[180:183], v[114:117]
	v_mfma_f32_16x16x32_bf16 v[102:105], v[158:161], v[192:195], v[102:105]
	v_mfma_f32_16x16x32_bf16 v[98:101], v[166:169], v[192:195], v[98:101]
	v_mfma_f32_16x16x32_bf16 v[86:89], v[158:161], v[200:203], v[86:89]
	v_mfma_f32_16x16x32_bf16 v[82:85], v[166:169], v[200:203], v[82:85]
	v_mfma_f32_16x16x32_bf16 v[70:73], v[158:161], v[208:211], v[70:73]
	v_mfma_f32_16x16x32_bf16 v[66:69], v[166:169], v[208:211], v[66:69]
	v_mfma_f32_16x16x32_bf16 v[118:121], v[162:165], v[184:187], v[118:121]
	v_mfma_f32_16x16x32_bf16 v[114:117], v[176:179], v[184:187], v[114:117]
	v_mfma_f32_16x16x32_bf16 v[102:105], v[162:165], v[196:199], v[102:105]
	v_mfma_f32_16x16x32_bf16 v[98:101], v[176:179], v[196:199], v[98:101]
	v_mfma_f32_16x16x32_bf16 v[86:89], v[162:165], v[204:207], v[86:89]
	v_mfma_f32_16x16x32_bf16 v[82:85], v[176:179], v[204:207], v[82:85]
	v_mfma_f32_16x16x32_bf16 v[70:73], v[162:165], v[212:215], v[70:73]
	v_mfma_f32_16x16x32_bf16 v[66:69], v[176:179], v[212:215], v[66:69]
	s_setprio 2
	s_barrier
	s_add_i32 s51, s36, 0x10000
	s_mov_b32 m0, s51
	ds_read_b128 v[180:183], v175 offset:16384
	ds_read_b128 v[184:187], v175 offset:17408
	ds_read_b128 v[192:195], v175 offset:18432
	ds_read_b128 v[196:199], v175 offset:19456
	ds_read_b128 v[200:203], v175 offset:20480
	ds_read_b128 v[204:207], v175 offset:21504
	ds_read_b128 v[208:211], v175 offset:22528
	ds_read_b128 v[212:215], v175 offset:23552
	global_load_lds_dwordx4 v0, s[26:27]
	s_add_i32 m0, s51, 0x2000
	s_add_u32 s52, s26, 0x40000
	global_load_lds_dwordx4 v142, s[26:27]
	s_addc_u32 s53, s27, 0
	s_add_i32 s51, s36, 0x14000
	s_mov_b32 m0, s51
	s_nop 0
	global_load_lds_dwordx4 v0, s[52:53]
	s_add_i32 m0, s51, 0x2000
	s_nop 0
	global_load_lds_dwordx4 v142, s[52:53]
	s_mov_b32 m0, s38
	s_nop 0
	global_load_lds_dwordx4 v146, s[28:29]
	s_waitcnt vmcnt(7)
	s_waitcnt lgkmcnt(0)
	s_barrier
	s_setprio 1
	s_waitcnt lgkmcnt(0)
	v_mfma_f32_16x16x32_bf16 v[62:65], v[130:133], v[180:183], v[62:65]
	v_mfma_f32_16x16x32_bf16 v[58:61], v[138:141], v[180:183], v[58:61]
	v_mfma_f32_16x16x32_bf16 v[46:49], v[130:133], v[192:195], v[46:49]
	v_mfma_f32_16x16x32_bf16 v[42:45], v[138:141], v[192:195], v[42:45]
	v_mfma_f32_16x16x32_bf16 v[30:33], v[130:133], v[200:203], v[30:33]
	v_mfma_f32_16x16x32_bf16 v[26:29], v[138:141], v[200:203], v[26:29]
	v_mfma_f32_16x16x32_bf16 v[14:17], v[130:133], v[208:211], v[14:17]
	v_mfma_f32_16x16x32_bf16 v[10:13], v[138:141], v[208:211], v[10:13]
	v_mfma_f32_16x16x32_bf16 v[62:65], v[134:137], v[184:187], v[62:65]
	v_mfma_f32_16x16x32_bf16 v[58:61], v[154:157], v[184:187], v[58:61]
	v_mfma_f32_16x16x32_bf16 v[46:49], v[134:137], v[196:199], v[46:49]
	v_mfma_f32_16x16x32_bf16 v[42:45], v[154:157], v[196:199], v[42:45]
	v_mfma_f32_16x16x32_bf16 v[30:33], v[134:137], v[204:207], v[30:33]
	v_mfma_f32_16x16x32_bf16 v[26:29], v[154:157], v[204:207], v[26:29]
	v_mfma_f32_16x16x32_bf16 v[14:17], v[134:137], v[212:215], v[14:17]
	v_mfma_f32_16x16x32_bf16 v[10:13], v[154:157], v[212:215], v[10:13]
	s_setprio 0
	s_setprio 1
	v_mfma_f32_16x16x32_bf16 v[54:57], v[158:161], v[180:183], v[54:57]
	v_mfma_f32_16x16x32_bf16 v[50:53], v[166:169], v[180:183], v[50:53]
	v_mfma_f32_16x16x32_bf16 v[38:41], v[158:161], v[192:195], v[38:41]
	v_mfma_f32_16x16x32_bf16 v[34:37], v[166:169], v[192:195], v[34:37]
	v_mfma_f32_16x16x32_bf16 v[22:25], v[158:161], v[200:203], v[22:25]
	v_mfma_f32_16x16x32_bf16 v[18:21], v[166:169], v[200:203], v[18:21]
	v_mfma_f32_16x16x32_bf16 v[6:9], v[158:161], v[208:211], v[6:9]
	v_mfma_f32_16x16x32_bf16 v[2:5], v[166:169], v[208:211], v[2:5]
	v_mfma_f32_16x16x32_bf16 v[54:57], v[162:165], v[184:187], v[54:57]
	v_mfma_f32_16x16x32_bf16 v[50:53], v[176:179], v[184:187], v[50:53]
	v_mfma_f32_16x16x32_bf16 v[38:41], v[162:165], v[196:199], v[38:41]
	v_mfma_f32_16x16x32_bf16 v[34:37], v[176:179], v[196:199], v[34:37]
	v_mfma_f32_16x16x32_bf16 v[22:25], v[162:165], v[204:207], v[22:25]
	v_mfma_f32_16x16x32_bf16 v[18:21], v[176:179], v[204:207], v[18:21]
	v_mfma_f32_16x16x32_bf16 v[6:9], v[162:165], v[212:215], v[6:9]
	v_mfma_f32_16x16x32_bf16 v[2:5], v[176:179], v[212:215], v[2:5]
	s_setprio 2
	s_barrier
	s_mov_b32 m0, s39
	ds_read_b128 v[130:133], v188 offset:32768
	ds_read_b128 v[134:137], v188 offset:33792
	ds_read_b128 v[138:141], v188 offset:34816
	ds_read_b128 v[154:157], v188 offset:35840
	ds_read_b128 v[158:161], v188 offset:49152
	ds_read_b128 v[162:165], v188 offset:50176
	ds_read_b128 v[166:169], v188 offset:51200
	ds_read_b128 v[176:179], v188 offset:52224
	ds_read_b128 v[180:183], v175 offset:32768
	ds_read_b128 v[184:187], v175 offset:33792
	ds_read_b128 v[192:195], v175 offset:34816
	ds_read_b128 v[196:199], v175 offset:35840
	ds_read_b128 v[200:203], v175 offset:36864
	ds_read_b128 v[204:207], v175 offset:37888
	ds_read_b128 v[208:211], v175 offset:38912
	ds_read_b128 v[212:215], v175 offset:39936
	global_load_lds_dwordx4 v144, s[28:29]
	s_add_u32 s28, s28, 0x40000
	s_addc_u32 s29, s29, 0
	s_mov_b32 m0, s40
	s_nop 0
	global_load_lds_dwordx4 v146, s[28:29]
	s_mov_b32 m0, s41
	s_nop 0
	global_load_lds_dwordx4 v144, s[28:29]
	s_waitcnt vmcnt(8)
	s_waitcnt lgkmcnt(0)
	s_barrier
	s_setprio 1
	s_waitcnt lgkmcnt(0)
	v_mfma_f32_16x16x32_bf16 v[126:129], v[130:133], v[180:183], v[126:129]
	v_mfma_f32_16x16x32_bf16 v[122:125], v[138:141], v[180:183], v[122:125]
	v_mfma_f32_16x16x32_bf16 v[110:113], v[130:133], v[192:195], v[110:113]
	v_mfma_f32_16x16x32_bf16 v[106:109], v[138:141], v[192:195], v[106:109]
	v_mfma_f32_16x16x32_bf16 v[94:97], v[130:133], v[200:203], v[94:97]
	v_mfma_f32_16x16x32_bf16 v[90:93], v[138:141], v[200:203], v[90:93]
	v_mfma_f32_16x16x32_bf16 v[78:81], v[130:133], v[208:211], v[78:81]
	v_mfma_f32_16x16x32_bf16 v[74:77], v[138:141], v[208:211], v[74:77]
	v_mfma_f32_16x16x32_bf16 v[126:129], v[134:137], v[184:187], v[126:129]
	v_mfma_f32_16x16x32_bf16 v[122:125], v[154:157], v[184:187], v[122:125]
	v_mfma_f32_16x16x32_bf16 v[110:113], v[134:137], v[196:199], v[110:113]
	v_mfma_f32_16x16x32_bf16 v[106:109], v[154:157], v[196:199], v[106:109]
	v_mfma_f32_16x16x32_bf16 v[94:97], v[134:137], v[204:207], v[94:97]
	v_mfma_f32_16x16x32_bf16 v[90:93], v[154:157], v[204:207], v[90:93]
	v_mfma_f32_16x16x32_bf16 v[78:81], v[134:137], v[212:215], v[78:81]
	v_mfma_f32_16x16x32_bf16 v[74:77], v[154:157], v[212:215], v[74:77]
	s_setprio 0
	s_setprio 1
	v_mfma_f32_16x16x32_bf16 v[118:121], v[158:161], v[180:183], v[118:121]
	v_mfma_f32_16x16x32_bf16 v[114:117], v[166:169], v[180:183], v[114:117]
	v_mfma_f32_16x16x32_bf16 v[102:105], v[158:161], v[192:195], v[102:105]
	v_mfma_f32_16x16x32_bf16 v[98:101], v[166:169], v[192:195], v[98:101]
	v_mfma_f32_16x16x32_bf16 v[86:89], v[158:161], v[200:203], v[86:89]
	v_mfma_f32_16x16x32_bf16 v[82:85], v[166:169], v[200:203], v[82:85]
	v_mfma_f32_16x16x32_bf16 v[70:73], v[158:161], v[208:211], v[70:73]
	v_mfma_f32_16x16x32_bf16 v[66:69], v[166:169], v[208:211], v[66:69]
	v_mfma_f32_16x16x32_bf16 v[118:121], v[162:165], v[184:187], v[118:121]
	v_mfma_f32_16x16x32_bf16 v[114:117], v[176:179], v[184:187], v[114:117]
	v_mfma_f32_16x16x32_bf16 v[102:105], v[162:165], v[196:199], v[102:105]
	v_mfma_f32_16x16x32_bf16 v[98:101], v[176:179], v[196:199], v[98:101]
	v_mfma_f32_16x16x32_bf16 v[86:89], v[162:165], v[204:207], v[86:89]
	v_mfma_f32_16x16x32_bf16 v[82:85], v[176:179], v[204:207], v[82:85]
	v_mfma_f32_16x16x32_bf16 v[70:73], v[162:165], v[212:215], v[70:73]
	v_mfma_f32_16x16x32_bf16 v[66:69], v[176:179], v[212:215], v[66:69]
	s_setprio 2
	s_barrier
	s_add_u32 s26, s26, 0x80
	s_addc_u32 s27, s27, 0
	s_add_i32 s51, s36, 0x18000
	s_mov_b32 m0, s51
	ds_read_b128 v[180:183], v175 offset:49152
	ds_read_b128 v[184:187], v175 offset:50176
	ds_read_b128 v[192:195], v175 offset:51200
	ds_read_b128 v[196:199], v175 offset:52224
	ds_read_b128 v[200:203], v175 offset:53248
	ds_read_b128 v[204:207], v175 offset:54272
	ds_read_b128 v[208:211], v175 offset:55296
	ds_read_b128 v[212:215], v175 offset:56320
	global_load_lds_dwordx4 v0, s[26:27]
	s_add_i32 m0, s51, 0x2000
	s_add_u32 s52, s26, 0x40000
	global_load_lds_dwordx4 v142, s[26:27]
	s_addc_u32 s53, s27, 0
	s_add_i32 s51, s36, 0x1c000
	s_mov_b32 m0, s51
	s_add_u32 s28, s28, 0xfffc0080
	global_load_lds_dwordx4 v0, s[52:53]
	s_addc_u32 s29, s29, -1
	s_add_i32 m0, s51, 0x2000
	s_nop 0
	global_load_lds_dwordx4 v142, s[52:53]
	s_mov_b32 m0, s42
	s_nop 0
	global_load_lds_dwordx4 v146, s[28:29]
	s_waitcnt vmcnt(7)
	s_waitcnt lgkmcnt(0)
	s_barrier
	s_setprio 1
	s_waitcnt lgkmcnt(0)
	v_mfma_f32_16x16x32_bf16 v[62:65], v[130:133], v[180:183], v[62:65]
	v_mfma_f32_16x16x32_bf16 v[58:61], v[138:141], v[180:183], v[58:61]
	v_mfma_f32_16x16x32_bf16 v[46:49], v[130:133], v[192:195], v[46:49]
	v_mfma_f32_16x16x32_bf16 v[42:45], v[138:141], v[192:195], v[42:45]
	v_mfma_f32_16x16x32_bf16 v[30:33], v[130:133], v[200:203], v[30:33]
	v_mfma_f32_16x16x32_bf16 v[26:29], v[138:141], v[200:203], v[26:29]
	v_mfma_f32_16x16x32_bf16 v[14:17], v[130:133], v[208:211], v[14:17]
	v_mfma_f32_16x16x32_bf16 v[10:13], v[138:141], v[208:211], v[10:13]
	v_mfma_f32_16x16x32_bf16 v[62:65], v[134:137], v[184:187], v[62:65]
	v_mfma_f32_16x16x32_bf16 v[58:61], v[154:157], v[184:187], v[58:61]
	v_mfma_f32_16x16x32_bf16 v[46:49], v[134:137], v[196:199], v[46:49]
	v_mfma_f32_16x16x32_bf16 v[42:45], v[154:157], v[196:199], v[42:45]
	v_mfma_f32_16x16x32_bf16 v[30:33], v[134:137], v[204:207], v[30:33]
	v_mfma_f32_16x16x32_bf16 v[26:29], v[154:157], v[204:207], v[26:29]
	v_mfma_f32_16x16x32_bf16 v[14:17], v[134:137], v[212:215], v[14:17]
	v_mfma_f32_16x16x32_bf16 v[10:13], v[154:157], v[212:215], v[10:13]
	s_setprio 0
	s_setprio 1
	v_mfma_f32_16x16x32_bf16 v[54:57], v[158:161], v[180:183], v[54:57]
	v_mfma_f32_16x16x32_bf16 v[50:53], v[166:169], v[180:183], v[50:53]
	v_mfma_f32_16x16x32_bf16 v[38:41], v[158:161], v[192:195], v[38:41]
	v_mfma_f32_16x16x32_bf16 v[34:37], v[166:169], v[192:195], v[34:37]
	v_mfma_f32_16x16x32_bf16 v[22:25], v[158:161], v[200:203], v[22:25]
	v_mfma_f32_16x16x32_bf16 v[18:21], v[166:169], v[200:203], v[18:21]
	v_mfma_f32_16x16x32_bf16 v[6:9], v[158:161], v[208:211], v[6:9]
	v_mfma_f32_16x16x32_bf16 v[2:5], v[166:169], v[208:211], v[2:5]
	v_mfma_f32_16x16x32_bf16 v[54:57], v[162:165], v[184:187], v[54:57]
	v_mfma_f32_16x16x32_bf16 v[50:53], v[176:179], v[184:187], v[50:53]
	v_mfma_f32_16x16x32_bf16 v[38:41], v[162:165], v[196:199], v[38:41]
	v_mfma_f32_16x16x32_bf16 v[34:37], v[176:179], v[196:199], v[34:37]
	v_mfma_f32_16x16x32_bf16 v[22:25], v[162:165], v[204:207], v[22:25]
	v_mfma_f32_16x16x32_bf16 v[18:21], v[176:179], v[204:207], v[18:21]
	v_mfma_f32_16x16x32_bf16 v[6:9], v[162:165], v[212:215], v[6:9]
	v_mfma_f32_16x16x32_bf16 v[2:5], v[176:179], v[212:215], v[2:5]
	s_setprio 2
	s_barrier
	s_add_i32 s50, s50, 2
	s_add_u32 s24, s24, 0x100
	s_addc_u32 s25, s25, 0
	s_add_u32 s48, s48, 0x100
	s_addc_u32 s49, s49, 0
	s_cmp_gt_u32 s50, 13
	s_cbranch_scc0 .LBB0_290
	s_and_b64 vcc, exec, s[12:13]
	s_cbranch_vccz .LBB0_293
	s_barrier

.LBB0_331:
	s_add_i32 s68, s34, 2
	s_add_u32 s69, s30, 0x80
	s_addc_u32 s35, s31, 0
	s_mov_b32 m0, s50
	ds_read_b128 v[130:133], v210
	ds_read_b128 v[134:137], v210 offset:1024
	ds_read_b128 v[138:141], v210 offset:2048
	ds_read_b128 v[142:145], v210 offset:3072
	ds_read_b128 v[146:149], v210 offset:16384
	ds_read_b128 v[150:153], v210 offset:17408
	ds_read_b128 v[154:157], v210 offset:18432
	ds_read_b128 v[158:161], v210 offset:19456
	ds_read_b128 v[162:165], v247
	ds_read_b128 v[166:169], v247 offset:1024
	ds_read_b128 v[170:173], v247 offset:2048
	ds_read_b128 v[174:177], v247 offset:3072
	ds_read_b128 v[178:181], v247 offset:4096
	ds_read_b128 v[182:185], v247 offset:5120
	ds_read_b128 v[202:205], v247 offset:6144
	ds_read_b128 v[206:209], v247 offset:7168
	global_load_lds_dwordx4 v188, s[30:31]
	s_add_i32 m0, s43, 0xc000
	s_nop 0
	global_load_lds_dwordx4 v198, s[30:31]
	s_add_i32 m0, s43, 0xe000
	s_cmp_eq_u32 s51, s34
	global_load_lds_dwordx4 v200, s[30:31]
	s_cselect_b32 s35, s11, s35
	s_cselect_b32 s34, s10, s69
	s_cselect_b32 s71, s13, s67
	s_cselect_b32 s70, s12, s66
	s_waitcnt vmcnt(8)
	s_waitcnt lgkmcnt(0)
	s_barrier
	s_setprio 1
	s_waitcnt lgkmcnt(0)
	v_mfma_f32_16x16x32_bf16 v[126:129], v[130:133], v[162:165], v[126:129]
	v_mfma_f32_16x16x32_bf16 v[122:125], v[138:141], v[162:165], v[122:125]
	v_mfma_f32_16x16x32_bf16 v[110:113], v[130:133], v[170:173], v[110:113]
	v_mfma_f32_16x16x32_bf16 v[106:109], v[138:141], v[170:173], v[106:109]
	v_mfma_f32_16x16x32_bf16 v[94:97], v[130:133], v[178:181], v[94:97]
	v_mfma_f32_16x16x32_bf16 v[90:93], v[138:141], v[178:181], v[90:93]
	v_mfma_f32_16x16x32_bf16 v[78:81], v[130:133], v[202:205], v[78:81]
	v_mfma_f32_16x16x32_bf16 v[74:77], v[138:141], v[202:205], v[74:77]
	v_mfma_f32_16x16x32_bf16 v[126:129], v[134:137], v[166:169], v[126:129]
	v_mfma_f32_16x16x32_bf16 v[122:125], v[142:145], v[166:169], v[122:125]
	v_mfma_f32_16x16x32_bf16 v[110:113], v[134:137], v[174:177], v[110:113]
	v_mfma_f32_16x16x32_bf16 v[106:109], v[142:145], v[174:177], v[106:109]
	v_mfma_f32_16x16x32_bf16 v[94:97], v[134:137], v[182:185], v[94:97]
	v_mfma_f32_16x16x32_bf16 v[90:93], v[142:145], v[182:185], v[90:93]
	v_mfma_f32_16x16x32_bf16 v[78:81], v[134:137], v[206:209], v[78:81]
	v_mfma_f32_16x16x32_bf16 v[74:77], v[142:145], v[206:209], v[74:77]
	s_setprio 0
	s_setprio 1
	v_mfma_f32_16x16x32_bf16 v[118:121], v[146:149], v[162:165], v[118:121]
	v_mfma_f32_16x16x32_bf16 v[114:117], v[154:157], v[162:165], v[114:117]
	v_mfma_f32_16x16x32_bf16 v[102:105], v[146:149], v[170:173], v[102:105]
	v_mfma_f32_16x16x32_bf16 v[98:101], v[154:157], v[170:173], v[98:101]
	v_mfma_f32_16x16x32_bf16 v[86:89], v[146:149], v[178:181], v[86:89]
	v_mfma_f32_16x16x32_bf16 v[82:85], v[154:157], v[178:181], v[82:85]
	v_mfma_f32_16x16x32_bf16 v[70:73], v[146:149], v[202:205], v[70:73]
	v_mfma_f32_16x16x32_bf16 v[66:69], v[154:157], v[202:205], v[66:69]
	v_mfma_f32_16x16x32_bf16 v[118:121], v[150:153], v[166:169], v[118:121]
	v_mfma_f32_16x16x32_bf16 v[114:117], v[158:161], v[166:169], v[114:117]
	v_mfma_f32_16x16x32_bf16 v[102:105], v[150:153], v[174:177], v[102:105]
	v_mfma_f32_16x16x32_bf16 v[98:101], v[158:161], v[174:177], v[98:101]
	v_mfma_f32_16x16x32_bf16 v[86:89], v[150:153], v[182:185], v[86:89]
	v_mfma_f32_16x16x32_bf16 v[82:85], v[158:161], v[182:185], v[82:85]
	v_mfma_f32_16x16x32_bf16 v[70:73], v[150:153], v[206:209], v[70:73]
	v_mfma_f32_16x16x32_bf16 v[66:69], v[158:161], v[206:209], v[66:69]
	s_setprio 2
	s_barrier
	s_add_i32 s72, s38, 0x10000
	s_mov_b32 m0, s72
	ds_read_b128 v[162:165], v247 offset:16384
	ds_read_b128 v[166:169], v247 offset:17408
	ds_read_b128 v[170:173], v247 offset:18432
	ds_read_b128 v[174:177], v247 offset:19456
	ds_read_b128 v[178:181], v247 offset:20480
	ds_read_b128 v[182:185], v247 offset:21504
	ds_read_b128 v[202:205], v247 offset:22528
	ds_read_b128 v[206:209], v247 offset:23552
	global_load_lds_dwordx4 v0, s[70:71]
	s_add_i32 m0, s72, 0x2000
	s_add_i32 s72, s38, 0x14000
	global_load_lds_dwordx4 v192, s[70:71]
	s_add_u32 s70, s70, s22
	s_addc_u32 s71, s71, 0
	s_mov_b32 m0, s72
	s_nop 0
	global_load_lds_dwordx4 v0, s[70:71]
	s_add_i32 m0, s72, 0x2000
	s_nop 0
	global_load_lds_dwordx4 v192, s[70:71]
	s_mov_b32 m0, s43
	s_nop 0
	global_load_lds_dwordx4 v186, s[34:35]
	s_waitcnt vmcnt(7)
	s_waitcnt lgkmcnt(0)
	s_barrier
	s_setprio 1
	s_waitcnt lgkmcnt(0)
	v_mfma_f32_16x16x32_bf16 v[62:65], v[130:133], v[162:165], v[62:65]
	v_mfma_f32_16x16x32_bf16 v[58:61], v[138:141], v[162:165], v[58:61]
	v_mfma_f32_16x16x32_bf16 v[46:49], v[130:133], v[170:173], v[46:49]
	v_mfma_f32_16x16x32_bf16 v[42:45], v[138:141], v[170:173], v[42:45]
	v_mfma_f32_16x16x32_bf16 v[30:33], v[130:133], v[178:181], v[30:33]
	v_mfma_f32_16x16x32_bf16 v[26:29], v[138:141], v[178:181], v[26:29]
	v_mfma_f32_16x16x32_bf16 v[14:17], v[130:133], v[202:205], v[14:17]
	v_mfma_f32_16x16x32_bf16 v[10:13], v[138:141], v[202:205], v[10:13]
	v_mfma_f32_16x16x32_bf16 v[62:65], v[134:137], v[166:169], v[62:65]
	v_mfma_f32_16x16x32_bf16 v[58:61], v[142:145], v[166:169], v[58:61]
	v_mfma_f32_16x16x32_bf16 v[46:49], v[134:137], v[174:177], v[46:49]
	v_mfma_f32_16x16x32_bf16 v[42:45], v[142:145], v[174:177], v[42:45]
	v_mfma_f32_16x16x32_bf16 v[30:33], v[134:137], v[182:185], v[30:33]
	v_mfma_f32_16x16x32_bf16 v[26:29], v[142:145], v[182:185], v[26:29]
	v_mfma_f32_16x16x32_bf16 v[14:17], v[134:137], v[206:209], v[14:17]
	v_mfma_f32_16x16x32_bf16 v[10:13], v[142:145], v[206:209], v[10:13]
	s_setprio 0
	s_setprio 1
	v_mfma_f32_16x16x32_bf16 v[54:57], v[146:149], v[162:165], v[54:57]
	v_mfma_f32_16x16x32_bf16 v[50:53], v[154:157], v[162:165], v[50:53]
	v_mfma_f32_16x16x32_bf16 v[38:41], v[146:149], v[170:173], v[38:41]
	v_mfma_f32_16x16x32_bf16 v[34:37], v[154:157], v[170:173], v[34:37]
	v_mfma_f32_16x16x32_bf16 v[22:25], v[146:149], v[178:181], v[22:25]
	v_mfma_f32_16x16x32_bf16 v[18:21], v[154:157], v[178:181], v[18:21]
	v_mfma_f32_16x16x32_bf16 v[6:9], v[146:149], v[202:205], v[6:9]
	v_mfma_f32_16x16x32_bf16 v[2:5], v[154:157], v[202:205], v[2:5]
	v_mfma_f32_16x16x32_bf16 v[54:57], v[150:153], v[166:169], v[54:57]
	v_mfma_f32_16x16x32_bf16 v[50:53], v[158:161], v[166:169], v[50:53]
	v_mfma_f32_16x16x32_bf16 v[38:41], v[150:153], v[174:177], v[38:41]
	v_mfma_f32_16x16x32_bf16 v[34:37], v[158:161], v[174:177], v[34:37]
	v_mfma_f32_16x16x32_bf16 v[22:25], v[150:153], v[182:185], v[22:25]
	v_mfma_f32_16x16x32_bf16 v[18:21], v[158:161], v[182:185], v[18:21]
	v_mfma_f32_16x16x32_bf16 v[6:9], v[150:153], v[206:209], v[6:9]
	v_mfma_f32_16x16x32_bf16 v[2:5], v[158:161], v[206:209], v[2:5]
	s_setprio 2
	s_barrier
	s_mov_b32 m0, s44
	ds_read_b128 v[130:133], v210 offset:32768
	ds_read_b128 v[134:137], v210 offset:33792
	ds_read_b128 v[138:141], v210 offset:34816
	ds_read_b128 v[142:145], v210 offset:35840
	ds_read_b128 v[146:149], v210 offset:49152
	ds_read_b128 v[150:153], v210 offset:50176
	ds_read_b128 v[154:157], v210 offset:51200
	ds_read_b128 v[158:161], v210 offset:52224
	ds_read_b128 v[162:165], v247 offset:32768
	ds_read_b128 v[166:169], v247 offset:33792
	ds_read_b128 v[170:173], v247 offset:34816
	ds_read_b128 v[174:177], v247 offset:35840
	ds_read_b128 v[178:181], v247 offset:36864
	ds_read_b128 v[182:185], v247 offset:37888
	ds_read_b128 v[202:205], v247 offset:38912
	ds_read_b128 v[206:209], v247 offset:39936
	global_load_lds_dwordx4 v188, s[34:35]
	s_add_u32 s34, s34, s22
	s_addc_u32 s35, s35, 0
	s_mov_b32 m0, s45
	s_nop 0
	global_load_lds_dwordx4 v186, s[34:35]
	s_mov_b32 m0, s46
	s_nop 0
	global_load_lds_dwordx4 v188, s[34:35]
	s_waitcnt vmcnt(8)
	s_waitcnt lgkmcnt(0)
	s_barrier
	s_setprio 1
	s_waitcnt lgkmcnt(0)
	v_mfma_f32_16x16x32_bf16 v[126:129], v[130:133], v[162:165], v[126:129]
	v_mfma_f32_16x16x32_bf16 v[122:125], v[138:141], v[162:165], v[122:125]
	v_mfma_f32_16x16x32_bf16 v[110:113], v[130:133], v[170:173], v[110:113]
	v_mfma_f32_16x16x32_bf16 v[106:109], v[138:141], v[170:173], v[106:109]
	v_mfma_f32_16x16x32_bf16 v[94:97], v[130:133], v[178:181], v[94:97]
	v_mfma_f32_16x16x32_bf16 v[90:93], v[138:141], v[178:181], v[90:93]
	v_mfma_f32_16x16x32_bf16 v[78:81], v[130:133], v[202:205], v[78:81]
	v_mfma_f32_16x16x32_bf16 v[74:77], v[138:141], v[202:205], v[74:77]
	v_mfma_f32_16x16x32_bf16 v[126:129], v[134:137], v[166:169], v[126:129]
	v_mfma_f32_16x16x32_bf16 v[122:125], v[142:145], v[166:169], v[122:125]
	v_mfma_f32_16x16x32_bf16 v[110:113], v[134:137], v[174:177], v[110:113]
	v_mfma_f32_16x16x32_bf16 v[106:109], v[142:145], v[174:177], v[106:109]
	v_mfma_f32_16x16x32_bf16 v[94:97], v[134:137], v[182:185], v[94:97]
	v_mfma_f32_16x16x32_bf16 v[90:93], v[142:145], v[182:185], v[90:93]
	v_mfma_f32_16x16x32_bf16 v[78:81], v[134:137], v[206:209], v[78:81]
	v_mfma_f32_16x16x32_bf16 v[74:77], v[142:145], v[206:209], v[74:77]
	s_setprio 0
	s_setprio 1
	v_mfma_f32_16x16x32_bf16 v[118:121], v[146:149], v[162:165], v[118:121]
	v_mfma_f32_16x16x32_bf16 v[114:117], v[154:157], v[162:165], v[114:117]
	v_mfma_f32_16x16x32_bf16 v[102:105], v[146:149], v[170:173], v[102:105]
	v_mfma_f32_16x16x32_bf16 v[98:101], v[154:157], v[170:173], v[98:101]
	v_mfma_f32_16x16x32_bf16 v[86:89], v[146:149], v[178:181], v[86:89]
	v_mfma_f32_16x16x32_bf16 v[82:85], v[154:157], v[178:181], v[82:85]
	v_mfma_f32_16x16x32_bf16 v[70:73], v[146:149], v[202:205], v[70:73]
	v_mfma_f32_16x16x32_bf16 v[66:69], v[154:157], v[202:205], v[66:69]
	v_mfma_f32_16x16x32_bf16 v[118:121], v[150:153], v[166:169], v[118:121]
	v_mfma_f32_16x16x32_bf16 v[114:117], v[158:161], v[166:169], v[114:117]
	v_mfma_f32_16x16x32_bf16 v[102:105], v[150:153], v[174:177], v[102:105]
	v_mfma_f32_16x16x32_bf16 v[98:101], v[158:161], v[174:177], v[98:101]
	v_mfma_f32_16x16x32_bf16 v[86:89], v[150:153], v[182:185], v[86:89]
	v_mfma_f32_16x16x32_bf16 v[82:85], v[158:161], v[182:185], v[82:85]
	v_mfma_f32_16x16x32_bf16 v[70:73], v[150:153], v[206:209], v[70:73]
	v_mfma_f32_16x16x32_bf16 v[66:69], v[158:161], v[206:209], v[66:69]
	s_setprio 2
	s_barrier
	s_add_u32 s70, s70, 0x80
	s_addc_u32 s71, s71, 0
	s_add_i32 s72, s38, 0x1c000
	s_mov_b32 m0, s72
	ds_read_b128 v[162:165], v247 offset:49152
	ds_read_b128 v[166:169], v247 offset:50176
	ds_read_b128 v[170:173], v247 offset:51200
	ds_read_b128 v[174:177], v247 offset:52224
	ds_read_b128 v[178:181], v247 offset:53248
	ds_read_b128 v[182:185], v247 offset:54272
	ds_read_b128 v[202:205], v247 offset:55296
	ds_read_b128 v[206:209], v247 offset:56320
	global_load_lds_dwordx4 v0, s[70:71]
	s_add_i32 m0, s72, 0x2000
	s_add_i32 s72, s38, 0x18000
	global_load_lds_dwordx4 v192, s[70:71]
	s_sub_u32 s70, s70, s22
	s_subb_u32 s71, s71, 0
	s_mov_b32 m0, s72
	s_sub_u32 s34, s34, s22
	global_load_lds_dwordx4 v0, s[70:71]
	s_subb_u32 s35, s35, 0
	s_add_i32 m0, s72, 0x2000
	s_add_u32 s34, s34, 0x80
	global_load_lds_dwordx4 v192, s[70:71]
	s_addc_u32 s35, s35, 0
	s_mov_b32 m0, s49
	s_nop 0
	global_load_lds_dwordx4 v186, s[34:35]
	s_waitcnt vmcnt(7)
	s_waitcnt lgkmcnt(0)
	s_barrier
	s_setprio 1
	s_waitcnt lgkmcnt(0)
	v_mfma_f32_16x16x32_bf16 v[62:65], v[130:133], v[162:165], v[62:65]
	v_mfma_f32_16x16x32_bf16 v[58:61], v[138:141], v[162:165], v[58:61]
	v_mfma_f32_16x16x32_bf16 v[46:49], v[130:133], v[170:173], v[46:49]
	v_mfma_f32_16x16x32_bf16 v[42:45], v[138:141], v[170:173], v[42:45]
	v_mfma_f32_16x16x32_bf16 v[30:33], v[130:133], v[178:181], v[30:33]
	v_mfma_f32_16x16x32_bf16 v[26:29], v[138:141], v[178:181], v[26:29]
	v_mfma_f32_16x16x32_bf16 v[14:17], v[130:133], v[202:205], v[14:17]
	v_mfma_f32_16x16x32_bf16 v[10:13], v[138:141], v[202:205], v[10:13]
	v_mfma_f32_16x16x32_bf16 v[62:65], v[134:137], v[166:169], v[62:65]
	v_mfma_f32_16x16x32_bf16 v[58:61], v[142:145], v[166:169], v[58:61]
	v_mfma_f32_16x16x32_bf16 v[46:49], v[134:137], v[174:177], v[46:49]
	v_mfma_f32_16x16x32_bf16 v[42:45], v[142:145], v[174:177], v[42:45]
	v_mfma_f32_16x16x32_bf16 v[30:33], v[134:137], v[182:185], v[30:33]
	v_mfma_f32_16x16x32_bf16 v[26:29], v[142:145], v[182:185], v[26:29]
	v_mfma_f32_16x16x32_bf16 v[14:17], v[134:137], v[206:209], v[14:17]
	v_mfma_f32_16x16x32_bf16 v[10:13], v[142:145], v[206:209], v[10:13]
	s_setprio 0
	s_setprio 1
	v_mfma_f32_16x16x32_bf16 v[54:57], v[146:149], v[162:165], v[54:57]
	v_mfma_f32_16x16x32_bf16 v[50:53], v[154:157], v[162:165], v[50:53]
	v_mfma_f32_16x16x32_bf16 v[38:41], v[146:149], v[170:173], v[38:41]
	v_mfma_f32_16x16x32_bf16 v[34:37], v[154:157], v[170:173], v[34:37]
	v_mfma_f32_16x16x32_bf16 v[22:25], v[146:149], v[178:181], v[22:25]
	v_mfma_f32_16x16x32_bf16 v[18:21], v[154:157], v[178:181], v[18:21]
	v_mfma_f32_16x16x32_bf16 v[6:9], v[146:149], v[202:205], v[6:9]
	v_mfma_f32_16x16x32_bf16 v[2:5], v[154:157], v[202:205], v[2:5]
	v_mfma_f32_16x16x32_bf16 v[54:57], v[150:153], v[166:169], v[54:57]
	v_mfma_f32_16x16x32_bf16 v[50:53], v[158:161], v[166:169], v[50:53]
	v_mfma_f32_16x16x32_bf16 v[38:41], v[150:153], v[174:177], v[38:41]
	v_mfma_f32_16x16x32_bf16 v[34:37], v[158:161], v[174:177], v[34:37]
	v_mfma_f32_16x16x32_bf16 v[22:25], v[150:153], v[182:185], v[22:25]
	v_mfma_f32_16x16x32_bf16 v[18:21], v[158:161], v[182:185], v[18:21]
	v_mfma_f32_16x16x32_bf16 v[6:9], v[150:153], v[206:209], v[6:9]
	v_mfma_f32_16x16x32_bf16 v[2:5], v[158:161], v[206:209], v[2:5]
	s_setprio 2
	s_barrier
	s_add_u32 s30, s30, 0x100
	s_addc_u32 s31, s31, 0
	s_add_u32 s66, s66, 0x100
	s_addc_u32 s67, s67, 0
	s_cmp_ge_u32 s68, s48
	s_mov_b32 s34, s68
	s_cbranch_scc0 .LBB0_331
	v_lshl_add_u32 v204, s65, 8, v191
	v_lshl_or_b32 v202, s64, 8, v246
	v_or_b32_e32 v210, 16, v204
	v_or_b32_e32 v208, 32, v204
	v_or_b32_e32 v206, 48, v204
	s_andn2_b64 vcc, exec, s[28:29]
	v_ashrrev_i32_e32 v203, 31, v202
	v_ashrrev_i32_e32 v205, 31, v204
	v_ashrrev_i32_e32 v211, 31, v210
	v_ashrrev_i32_e32 v209, 31, v208
	v_ashrrev_i32_e32 v207, 31, v206
	s_cbranch_vccnz .LBB0_350
	s_cmp_lt_i32 s65, 64
	s_cselect_b32 s30, s19, s17
	s_cselect_b32 s31, s18, s16
	v_mov_b32_e32 v130, s31
	v_mov_b32_e32 v131, s30
	v_lshl_add_u64 v[212:213], v[202:203], 2, v[130:131]
	v_lshlrev_b64 v[130:131], 12, v[204:205]
	v_lshl_add_u64 v[130:131], v[212:213], 0, v[130:131]
	global_load_dwordx4 v[182:185], v[130:131], off offset:16 nt
	global_load_dwordx4 v[214:217], v[130:131], off nt
	global_load_dwordx4 v[178:181], v[130:131], off offset:528 nt
	global_load_dwordx4 v[218:221], v[130:131], off offset:512 nt
	v_lshlrev_b64 v[130:131], 12, v[210:211]
	v_lshl_add_u64 v[130:131], v[212:213], 0, v[130:131]
	global_load_dwordx4 v[170:173], v[130:131], off offset:16 nt
	global_load_dwordx4 v[174:177], v[130:131], off nt
	global_load_dwordx4 v[162:165], v[130:131], off offset:528 nt
	global_load_dwordx4 v[166:169], v[130:131], off offset:512 nt
	v_lshlrev_b64 v[130:131], 12, v[208:209]
	v_lshl_add_u64 v[130:131], v[212:213], 0, v[130:131]
	global_load_dwordx4 v[154:157], v[130:131], off offset:16 nt
	global_load_dwordx4 v[158:161], v[130:131], off nt
	global_load_dwordx4 v[138:141], v[130:131], off offset:528 nt
	global_load_dwordx4 v[146:149], v[130:131], off offset:512 nt
	v_lshlrev_b64 v[130:131], 12, v[206:207]
	v_lshl_add_u64 v[134:135], v[212:213], 0, v[130:131]
	global_load_dwordx4 v[142:145], v[134:135], off offset:16 nt
	global_load_dwordx4 v[150:153], v[134:135], off nt
	global_load_dwordx4 v[130:133], v[134:135], off offset:528 nt
	s_nop 0
	global_load_dwordx4 v[134:137], v[134:135], off offset:512 nt
	v_cmp_lt_i32_e32 vcc, v239, v244
	v_lshlrev_b64 v[224:225], 11, v[204:205]
	s_lshl_b32 s30, s64, 2
	v_cndmask_b32_e32 v195, v234, v239, vcc
	v_cmp_lt_i32_e32 vcc, v240, v244
	v_lshlrev_b32_e32 v248, 2, v195
	s_ashr_i32 s31, s30, 31
	v_cndmask_b32_e32 v195, v234, v240, vcc
	v_lshlrev_b32_e32 v249, 2, v195
	v_mov_b32_e32 v195, v194
	s_waitcnt vmcnt(0)
	v_pk_fma_f32 v[226:227], v[194:195], v[124:125], v[184:185]
	v_pk_fma_f32 v[184:185], v[196:197], v[122:123], v[182:183]
	v_pk_fma_f32 v[216:217], v[194:195], v[128:129], v[216:217]
	v_pk_fma_f32 v[214:215], v[196:197], v[126:127], v[214:215]
	v_pk_mul_f32 v[182:183], v[226:227], v[226:227]
	v_pk_mul_f32 v[250:251], v[184:185], v[184:185]
	v_pk_fma_f32 v[182:183], v[216:217], v[216:217], v[182:183]
	v_pk_fma_f32 v[250:251], v[214:215], v[214:215], v[250:251]
	v_add_f32_e32 v182, v182, v183
	v_add_f32_e32 v232, v250, v251
	v_add_f32_e32 v232, v232, v182
	v_cvt_pk_bf16_f32 v182, v214, v215
	v_lshl_add_u64 v[214:215], s[26:27], 0, v[224:225]
	v_cvt_pk_bf16_f32 v183, v216, v217
	v_cvt_pk_bf16_f32 v184, v184, v185
	v_cvt_pk_bf16_f32 v185, v226, v227
	v_lshl_add_u64 v[214:215], v[202:203], 1, v[214:215]
	v_pk_fma_f32 v[216:217], v[194:195], v[116:117], v[180:181]
	v_pk_fma_f32 v[180:181], v[196:197], v[114:115], v[178:179]
	global_store_dwordx4 v[214:215], v[182:185], off
	v_pk_mul_f32 v[178:179], v[216:217], v[216:217]
	s_nop 0
	v_pk_fma_f32 v[182:183], v[194:195], v[120:121], v[220:221]
	v_pk_fma_f32 v[184:185], v[196:197], v[118:119], v[218:219]
	v_pk_mul_f32 v[218:219], v[180:181], v[180:181]
	v_pk_fma_f32 v[178:179], v[182:183], v[182:183], v[178:179]
	v_pk_fma_f32 v[218:219], v[184:185], v[184:185], v[218:219]
	v_add_f32_e32 v178, v178, v179
	v_add_f32_e32 v218, v218, v219
	v_add_f32_e32 v178, v218, v178
	v_add_f32_e32 v218, v232, v178
	v_cvt_pk_bf16_f32 v178, v184, v185
	v_cvt_pk_bf16_f32 v179, v182, v183
	v_cvt_pk_bf16_f32 v180, v180, v181
	v_cvt_pk_bf16_f32 v181, v216, v217
	global_store_dwordx4 v[214:215], v[178:181], off offset:256
	ds_bpermute_b32 v178, v248, v218
	s_waitcnt lgkmcnt(0)
	v_add_f32_e32 v178, v218, v178
	ds_bpermute_b32 v179, v249, v178
	s_and_saveexec_b64 s[34:35], s[6:7]
	s_cbranch_execz .LBB0_335
	v_lshlrev_b64 v[180:181], 6, v[204:205]
	v_lshl_add_u64 v[180:181], s[24:25], 0, v[180:181]
	v_lshl_add_u64 v[180:181], s[30:31], 2, v[180:181]
	s_lshl_b32 s84, s47, 2
	v_lshl_add_u64 v[180:181], v[180:181], 0, s[84:85]
	s_waitcnt lgkmcnt(0)
	v_add_f32_e32 v178, v178, v179
	global_store_dword v[180:181], v178, off

.LBB0_394:
	s_add_u32 s12, s10, 0xfffc0080
	s_addc_u32 s13, s11, -1
	s_add_u32 s48, s10, 0xfffc0000
	s_addc_u32 s49, s11, -1
	s_mov_b32 m0, s74
	ds_read_b128 v[50:53], v216
	ds_read_b128 v[54:57], v216 offset:1024
	ds_read_b128 v[58:61], v216 offset:2048
	ds_read_b128 v[62:65], v216 offset:3072
	ds_read_b128 v[162:165], v216 offset:16384
	ds_read_b128 v[166:169], v216 offset:17408
	ds_read_b128 v[170:173], v216 offset:18432
	ds_read_b128 v[174:177], v216 offset:19456
	ds_read_b128 v[178:181], v184
	ds_read_b128 v[186:189], v184 offset:1024
	ds_read_b128 v[192:195], v184 offset:2048
	ds_read_b128 v[196:199], v184 offset:3072
	ds_read_b128 v[200:203], v184 offset:4096
	ds_read_b128 v[204:207], v184 offset:5120
	ds_read_b128 v[208:211], v184 offset:6144
	ds_read_b128 v[212:215], v184 offset:7168
	global_load_lds_dwordx4 v150, s[48:49]
	s_add_i32 m0, s41, 0xc000
	s_nop 0
	global_load_lds_dwordx4 v158, s[10:11]
	s_add_i32 m0, s41, 0xe000
	s_cmp_eq_u32 s46, 12
	global_load_lds_dwordx4 v160, s[10:11]
	s_cselect_b32 s15, s31, s13
	s_cselect_b32 s14, s38, s12
	s_cselect_b32 s13, s29, s45
	s_cselect_b32 s12, s39, s44
	s_waitcnt vmcnt(8)
	s_waitcnt lgkmcnt(0)
	s_barrier
	s_setprio 1
	s_waitcnt lgkmcnt(0)
	v_mfma_f32_16x16x32_bf16 v[142:145], v[50:53], v[178:181], v[142:145]
	v_mfma_f32_16x16x32_bf16 v[138:141], v[58:61], v[178:181], v[138:141]
	v_mfma_f32_16x16x32_bf16 v[126:129], v[50:53], v[192:195], v[126:129]
	v_mfma_f32_16x16x32_bf16 v[122:125], v[58:61], v[192:195], v[122:125]
	v_mfma_f32_16x16x32_bf16 v[110:113], v[50:53], v[200:203], v[110:113]
	v_mfma_f32_16x16x32_bf16 v[106:109], v[58:61], v[200:203], v[106:109]
	v_mfma_f32_16x16x32_bf16 v[94:97], v[50:53], v[208:211], v[94:97]
	v_mfma_f32_16x16x32_bf16 v[90:93], v[58:61], v[208:211], v[90:93]
	v_mfma_f32_16x16x32_bf16 v[142:145], v[54:57], v[186:189], v[142:145]
	v_mfma_f32_16x16x32_bf16 v[138:141], v[62:65], v[186:189], v[138:141]
	v_mfma_f32_16x16x32_bf16 v[126:129], v[54:57], v[196:199], v[126:129]
	v_mfma_f32_16x16x32_bf16 v[122:125], v[62:65], v[196:199], v[122:125]
	v_mfma_f32_16x16x32_bf16 v[110:113], v[54:57], v[204:207], v[110:113]
	v_mfma_f32_16x16x32_bf16 v[106:109], v[62:65], v[204:207], v[106:109]
	v_mfma_f32_16x16x32_bf16 v[94:97], v[54:57], v[212:215], v[94:97]
	v_mfma_f32_16x16x32_bf16 v[90:93], v[62:65], v[212:215], v[90:93]
	s_setprio 0
	s_setprio 1
	v_mfma_f32_16x16x32_bf16 v[134:137], v[162:165], v[178:181], v[134:137]
	v_mfma_f32_16x16x32_bf16 v[130:133], v[170:173], v[178:181], v[130:133]
	v_mfma_f32_16x16x32_bf16 v[118:121], v[162:165], v[192:195], v[118:121]
	v_mfma_f32_16x16x32_bf16 v[114:117], v[170:173], v[192:195], v[114:117]
	v_mfma_f32_16x16x32_bf16 v[102:105], v[162:165], v[200:203], v[102:105]
	v_mfma_f32_16x16x32_bf16 v[98:101], v[170:173], v[200:203], v[98:101]
	v_mfma_f32_16x16x32_bf16 v[86:89], v[162:165], v[208:211], v[86:89]
	v_mfma_f32_16x16x32_bf16 v[82:85], v[170:173], v[208:211], v[82:85]
	v_mfma_f32_16x16x32_bf16 v[134:137], v[166:169], v[186:189], v[134:137]
	v_mfma_f32_16x16x32_bf16 v[130:133], v[174:177], v[186:189], v[130:133]
	v_mfma_f32_16x16x32_bf16 v[118:121], v[166:169], v[196:199], v[118:121]
	v_mfma_f32_16x16x32_bf16 v[114:117], v[174:177], v[196:199], v[114:117]
	v_mfma_f32_16x16x32_bf16 v[102:105], v[166:169], v[204:207], v[102:105]
	v_mfma_f32_16x16x32_bf16 v[98:101], v[174:177], v[204:207], v[98:101]
	v_mfma_f32_16x16x32_bf16 v[86:89], v[166:169], v[212:215], v[86:89]
	v_mfma_f32_16x16x32_bf16 v[82:85], v[174:177], v[212:215], v[82:85]
	s_setprio 2
	s_barrier
	s_add_i32 s47, s68, 0x10000
	s_mov_b32 m0, s47
	ds_read_b128 v[178:181], v184 offset:16384
	ds_read_b128 v[186:189], v184 offset:17408
	ds_read_b128 v[192:195], v184 offset:18432
	ds_read_b128 v[196:199], v184 offset:19456
	ds_read_b128 v[200:203], v184 offset:20480
	ds_read_b128 v[204:207], v184 offset:21504
	ds_read_b128 v[208:211], v184 offset:22528
	ds_read_b128 v[212:215], v184 offset:23552
	global_load_lds_dwordx4 v148, s[12:13]
	s_add_i32 m0, s47, 0x2000
	s_add_u32 s48, s12, 0x40000
	global_load_lds_dwordx4 v152, s[12:13]
	s_addc_u32 s49, s13, 0
	s_add_i32 s47, s68, 0x14000
	s_mov_b32 m0, s47
	s_nop 0
	global_load_lds_dwordx4 v148, s[48:49]
	s_add_i32 m0, s47, 0x2000
	s_nop 0
	global_load_lds_dwordx4 v152, s[48:49]
	s_mov_b32 m0, s41
	s_nop 0
	global_load_lds_dwordx4 v146, s[14:15]
	s_waitcnt vmcnt(7)
	s_waitcnt lgkmcnt(0)
	s_barrier
	s_setprio 1
	s_waitcnt lgkmcnt(0)
	v_mfma_f32_16x16x32_bf16 v[78:81], v[50:53], v[178:181], v[78:81]
	v_mfma_f32_16x16x32_bf16 v[74:77], v[58:61], v[178:181], v[74:77]
	v_mfma_f32_16x16x32_bf16 v[46:49], v[50:53], v[192:195], v[46:49]
	v_mfma_f32_16x16x32_bf16 v[42:45], v[58:61], v[192:195], v[42:45]
	v_mfma_f32_16x16x32_bf16 v[30:33], v[50:53], v[200:203], v[30:33]
	v_mfma_f32_16x16x32_bf16 v[26:29], v[58:61], v[200:203], v[26:29]
	v_mfma_f32_16x16x32_bf16 v[14:17], v[50:53], v[208:211], v[14:17]
	v_mfma_f32_16x16x32_bf16 v[10:13], v[58:61], v[208:211], v[10:13]
	v_mfma_f32_16x16x32_bf16 v[78:81], v[54:57], v[186:189], v[78:81]
	v_mfma_f32_16x16x32_bf16 v[74:77], v[62:65], v[186:189], v[74:77]
	v_mfma_f32_16x16x32_bf16 v[46:49], v[54:57], v[196:199], v[46:49]
	v_mfma_f32_16x16x32_bf16 v[42:45], v[62:65], v[196:199], v[42:45]
	v_mfma_f32_16x16x32_bf16 v[30:33], v[54:57], v[204:207], v[30:33]
	v_mfma_f32_16x16x32_bf16 v[26:29], v[62:65], v[204:207], v[26:29]
	v_mfma_f32_16x16x32_bf16 v[14:17], v[54:57], v[212:215], v[14:17]
	v_mfma_f32_16x16x32_bf16 v[10:13], v[62:65], v[212:215], v[10:13]
	s_setprio 0
	s_setprio 1
	v_mfma_f32_16x16x32_bf16 v[38:41], v[162:165], v[192:195], v[38:41]
	v_mfma_f32_16x16x32_bf16 v[34:37], v[170:173], v[192:195], v[34:37]
	v_mfma_f32_16x16x32_bf16 v[22:25], v[162:165], v[200:203], v[22:25]
	v_mfma_f32_16x16x32_bf16 v[18:21], v[170:173], v[200:203], v[18:21]
	v_mfma_f32_16x16x32_bf16 v[6:9], v[162:165], v[208:211], v[6:9]
	v_mfma_f32_16x16x32_bf16 v[2:5], v[170:173], v[208:211], v[2:5]
	v_mfma_f32_16x16x32_bf16 v[50:53], v[162:165], v[178:181], v[70:73]
	v_mfma_f32_16x16x32_bf16 v[54:57], v[170:173], v[178:181], v[66:69]
	v_mfma_f32_16x16x32_bf16 v[38:41], v[166:169], v[196:199], v[38:41]
	v_mfma_f32_16x16x32_bf16 v[34:37], v[174:177], v[196:199], v[34:37]
	v_mfma_f32_16x16x32_bf16 v[22:25], v[166:169], v[204:207], v[22:25]
	v_mfma_f32_16x16x32_bf16 v[18:21], v[174:177], v[204:207], v[18:21]
	v_mfma_f32_16x16x32_bf16 v[6:9], v[166:169], v[212:215], v[6:9]
	v_mfma_f32_16x16x32_bf16 v[2:5], v[174:177], v[212:215], v[2:5]
	v_mfma_f32_16x16x32_bf16 v[50:53], v[166:169], v[186:189], v[50:53]
	v_mfma_f32_16x16x32_bf16 v[54:57], v[174:177], v[186:189], v[54:57]
	s_setprio 2
	s_barrier
	s_mov_b32 m0, s43
	ds_read_b128 v[58:61], v216 offset:32768
	ds_read_b128 v[62:65], v216 offset:33792
	ds_read_b128 v[66:69], v216 offset:34816
	ds_read_b128 v[70:73], v216 offset:35840
	ds_read_b128 v[162:165], v216 offset:49152
	ds_read_b128 v[166:169], v216 offset:50176
	ds_read_b128 v[170:173], v216 offset:51200
	ds_read_b128 v[174:177], v216 offset:52224
	ds_read_b128 v[178:181], v184 offset:32768
	ds_read_b128 v[186:189], v184 offset:33792
	ds_read_b128 v[192:195], v184 offset:34816
	ds_read_b128 v[196:199], v184 offset:35840
	ds_read_b128 v[200:203], v184 offset:36864
	ds_read_b128 v[204:207], v184 offset:37888
	ds_read_b128 v[208:211], v184 offset:38912
	ds_read_b128 v[212:215], v184 offset:39936
	global_load_lds_dwordx4 v150, s[14:15]
	s_add_u32 s14, s14, 0x40000
	s_addc_u32 s15, s15, 0
	s_mov_b32 m0, s69
	s_nop 0
	global_load_lds_dwordx4 v146, s[14:15]
	s_mov_b32 m0, s70
	s_nop 0
	global_load_lds_dwordx4 v150, s[14:15]
	s_waitcnt vmcnt(8)
	s_waitcnt lgkmcnt(0)
	s_barrier
	s_setprio 1
	s_waitcnt lgkmcnt(0)
	v_mfma_f32_16x16x32_bf16 v[142:145], v[58:61], v[178:181], v[142:145]
	v_mfma_f32_16x16x32_bf16 v[138:141], v[66:69], v[178:181], v[138:141]
	v_mfma_f32_16x16x32_bf16 v[126:129], v[58:61], v[192:195], v[126:129]
	v_mfma_f32_16x16x32_bf16 v[122:125], v[66:69], v[192:195], v[122:125]
	v_mfma_f32_16x16x32_bf16 v[110:113], v[58:61], v[200:203], v[110:113]
	v_mfma_f32_16x16x32_bf16 v[106:109], v[66:69], v[200:203], v[106:109]
	v_mfma_f32_16x16x32_bf16 v[94:97], v[58:61], v[208:211], v[94:97]
	v_mfma_f32_16x16x32_bf16 v[90:93], v[66:69], v[208:211], v[90:93]
	v_mfma_f32_16x16x32_bf16 v[142:145], v[62:65], v[186:189], v[142:145]
	v_mfma_f32_16x16x32_bf16 v[138:141], v[70:73], v[186:189], v[138:141]
	v_mfma_f32_16x16x32_bf16 v[126:129], v[62:65], v[196:199], v[126:129]
	v_mfma_f32_16x16x32_bf16 v[122:125], v[70:73], v[196:199], v[122:125]
	v_mfma_f32_16x16x32_bf16 v[110:113], v[62:65], v[204:207], v[110:113]
	v_mfma_f32_16x16x32_bf16 v[106:109], v[70:73], v[204:207], v[106:109]
	v_mfma_f32_16x16x32_bf16 v[94:97], v[62:65], v[212:215], v[94:97]
	v_mfma_f32_16x16x32_bf16 v[90:93], v[70:73], v[212:215], v[90:93]
	s_setprio 0
	s_setprio 1
	v_mfma_f32_16x16x32_bf16 v[134:137], v[162:165], v[178:181], v[134:137]
	v_mfma_f32_16x16x32_bf16 v[130:133], v[170:173], v[178:181], v[130:133]
	v_mfma_f32_16x16x32_bf16 v[118:121], v[162:165], v[192:195], v[118:121]
	v_mfma_f32_16x16x32_bf16 v[114:117], v[170:173], v[192:195], v[114:117]
	v_mfma_f32_16x16x32_bf16 v[102:105], v[162:165], v[200:203], v[102:105]
	v_mfma_f32_16x16x32_bf16 v[98:101], v[170:173], v[200:203], v[98:101]
	v_mfma_f32_16x16x32_bf16 v[86:89], v[162:165], v[208:211], v[86:89]
	v_mfma_f32_16x16x32_bf16 v[82:85], v[170:173], v[208:211], v[82:85]
	v_mfma_f32_16x16x32_bf16 v[134:137], v[166:169], v[186:189], v[134:137]
	v_mfma_f32_16x16x32_bf16 v[130:133], v[174:177], v[186:189], v[130:133]
	v_mfma_f32_16x16x32_bf16 v[118:121], v[166:169], v[196:199], v[118:121]
	v_mfma_f32_16x16x32_bf16 v[114:117], v[174:177], v[196:199], v[114:117]
	v_mfma_f32_16x16x32_bf16 v[102:105], v[166:169], v[204:207], v[102:105]
	v_mfma_f32_16x16x32_bf16 v[98:101], v[174:177], v[204:207], v[98:101]
	v_mfma_f32_16x16x32_bf16 v[86:89], v[166:169], v[212:215], v[86:89]
	v_mfma_f32_16x16x32_bf16 v[82:85], v[174:177], v[212:215], v[82:85]
	s_setprio 2
	s_barrier
	s_add_u32 s12, s12, 0x80
	s_addc_u32 s13, s13, 0
	s_add_i32 s47, s68, 0x18000
	s_mov_b32 m0, s47
	ds_read_b128 v[178:181], v184 offset:49152
	ds_read_b128 v[186:189], v184 offset:50176
	ds_read_b128 v[192:195], v184 offset:51200
	ds_read_b128 v[196:199], v184 offset:52224
	ds_read_b128 v[200:203], v184 offset:53248
	ds_read_b128 v[204:207], v184 offset:54272
	ds_read_b128 v[208:211], v184 offset:55296
	ds_read_b128 v[212:215], v184 offset:56320
	global_load_lds_dwordx4 v148, s[12:13]
	s_add_i32 m0, s47, 0x2000
	s_add_u32 s48, s12, 0x40000
	global_load_lds_dwordx4 v152, s[12:13]
	s_addc_u32 s49, s13, 0
	s_add_i32 s47, s68, 0x1c000
	s_mov_b32 m0, s47
	s_add_u32 s14, s14, 0xfffc0080
	global_load_lds_dwordx4 v148, s[48:49]
	s_addc_u32 s15, s15, -1
	s_add_i32 m0, s47, 0x2000
	s_nop 0
	global_load_lds_dwordx4 v152, s[48:49]
	s_mov_b32 m0, s73
	s_nop 0
	global_load_lds_dwordx4 v146, s[14:15]
	s_waitcnt vmcnt(7)
	s_waitcnt lgkmcnt(0)
	s_barrier
	s_setprio 1
	s_waitcnt lgkmcnt(0)
	v_mfma_f32_16x16x32_bf16 v[78:81], v[58:61], v[178:181], v[78:81]
	v_mfma_f32_16x16x32_bf16 v[74:77], v[66:69], v[178:181], v[74:77]
	v_mfma_f32_16x16x32_bf16 v[46:49], v[58:61], v[192:195], v[46:49]
	v_mfma_f32_16x16x32_bf16 v[42:45], v[66:69], v[192:195], v[42:45]
	v_mfma_f32_16x16x32_bf16 v[30:33], v[58:61], v[200:203], v[30:33]
	v_mfma_f32_16x16x32_bf16 v[26:29], v[66:69], v[200:203], v[26:29]
	v_mfma_f32_16x16x32_bf16 v[14:17], v[58:61], v[208:211], v[14:17]
	v_mfma_f32_16x16x32_bf16 v[10:13], v[66:69], v[208:211], v[10:13]
	v_mfma_f32_16x16x32_bf16 v[78:81], v[62:65], v[186:189], v[78:81]
	v_mfma_f32_16x16x32_bf16 v[74:77], v[70:73], v[186:189], v[74:77]
	v_mfma_f32_16x16x32_bf16 v[46:49], v[62:65], v[196:199], v[46:49]
	v_mfma_f32_16x16x32_bf16 v[42:45], v[70:73], v[196:199], v[42:45]
	v_mfma_f32_16x16x32_bf16 v[30:33], v[62:65], v[204:207], v[30:33]
	v_mfma_f32_16x16x32_bf16 v[26:29], v[70:73], v[204:207], v[26:29]
	v_mfma_f32_16x16x32_bf16 v[14:17], v[62:65], v[212:215], v[14:17]
	v_mfma_f32_16x16x32_bf16 v[10:13], v[70:73], v[212:215], v[10:13]
	s_setprio 0
	s_setprio 1
	v_mfma_f32_16x16x32_bf16 v[50:53], v[162:165], v[178:181], v[50:53]
	v_mfma_f32_16x16x32_bf16 v[70:73], v[166:169], v[186:189], v[50:53]
	v_mfma_f32_16x16x32_bf16 v[50:53], v[170:173], v[178:181], v[54:57]
	v_mfma_f32_16x16x32_bf16 v[38:41], v[162:165], v[192:195], v[38:41]
	v_mfma_f32_16x16x32_bf16 v[34:37], v[170:173], v[192:195], v[34:37]
	v_mfma_f32_16x16x32_bf16 v[22:25], v[162:165], v[200:203], v[22:25]
	v_mfma_f32_16x16x32_bf16 v[18:21], v[170:173], v[200:203], v[18:21]
	v_mfma_f32_16x16x32_bf16 v[6:9], v[162:165], v[208:211], v[6:9]
	v_mfma_f32_16x16x32_bf16 v[2:5], v[170:173], v[208:211], v[2:5]
	v_mfma_f32_16x16x32_bf16 v[66:69], v[174:177], v[186:189], v[50:53]
	v_mfma_f32_16x16x32_bf16 v[38:41], v[166:169], v[196:199], v[38:41]
	v_mfma_f32_16x16x32_bf16 v[34:37], v[174:177], v[196:199], v[34:37]
	v_mfma_f32_16x16x32_bf16 v[22:25], v[166:169], v[204:207], v[22:25]
	v_mfma_f32_16x16x32_bf16 v[18:21], v[174:177], v[204:207], v[18:21]
	v_mfma_f32_16x16x32_bf16 v[6:9], v[166:169], v[212:215], v[6:9]
	v_mfma_f32_16x16x32_bf16 v[2:5], v[174:177], v[212:215], v[2:5]
	s_setprio 2
	s_barrier
	s_add_i32 s46, s46, 2
	s_add_u32 s10, s10, 0x100
	s_addc_u32 s11, s11, 0
	s_add_u32 s44, s44, 0x100
	s_addc_u32 s45, s45, 0
	s_cmp_gt_u32 s46, 13
	s_cbranch_scc0 .LBB0_394
	s_and_b64 vcc, exec, s[24:25]
	s_cbranch_vccz .LBB0_397
	s_barrier

.LBB0_458:
	s_add_i32 s69, s38, 2
	s_add_u32 s70, s36, 0x80
	s_addc_u32 s39, s37, 0
	s_mov_b32 m0, s55
	ds_read_b128 v[130:133], v202
	ds_read_b128 v[134:137], v202 offset:1024
	ds_read_b128 v[138:141], v202 offset:2048
	ds_read_b128 v[142:145], v202 offset:3072
	ds_read_b128 v[146:149], v202 offset:16384
	ds_read_b128 v[150:153], v202 offset:17408
	ds_read_b128 v[154:157], v202 offset:18432
	ds_read_b128 v[158:161], v202 offset:19456
	ds_read_b128 v[162:165], v209
	ds_read_b128 v[166:169], v209 offset:1024
	ds_read_b128 v[170:173], v209 offset:2048
	ds_read_b128 v[186:189], v209 offset:3072
	ds_read_b128 v[192:195], v209 offset:4096
	ds_read_b128 v[196:199], v209 offset:5120
	ds_read_b128 v[210:213], v209 offset:6144
	ds_read_b128 v[214:217], v209 offset:7168
	global_load_lds_dwordx4 v176, s[36:37]
	s_add_i32 m0, s23, 0xc000
	s_nop 0
	global_load_lds_dwordx4 v182, s[36:37]
	s_add_i32 m0, s23, 0xe000
	s_cmp_eq_u32 s63, s38
	global_load_lds_dwordx4 v184, s[36:37]
	s_cselect_b32 s39, s27, s39
	s_cselect_b32 s38, s35, s70
	s_cselect_b32 s71, s25, s68
	s_cselect_b32 s70, s66, s67
	s_waitcnt vmcnt(8)
	s_waitcnt lgkmcnt(0)
	s_barrier
	s_setprio 1
	s_waitcnt lgkmcnt(0)
	v_mfma_f32_16x16x32_bf16 v[126:129], v[130:133], v[162:165], v[126:129]
	v_mfma_f32_16x16x32_bf16 v[122:125], v[138:141], v[162:165], v[122:125]
	v_mfma_f32_16x16x32_bf16 v[118:121], v[130:133], v[170:173], v[118:121]
	v_mfma_f32_16x16x32_bf16 v[114:117], v[138:141], v[170:173], v[114:117]
	v_mfma_f32_16x16x32_bf16 v[110:113], v[130:133], v[192:195], v[110:113]
	v_mfma_f32_16x16x32_bf16 v[106:109], v[138:141], v[192:195], v[106:109]
	v_mfma_f32_16x16x32_bf16 v[102:105], v[130:133], v[210:213], v[102:105]
	v_mfma_f32_16x16x32_bf16 v[98:101], v[138:141], v[210:213], v[98:101]
	v_mfma_f32_16x16x32_bf16 v[126:129], v[134:137], v[166:169], v[126:129]
	v_mfma_f32_16x16x32_bf16 v[122:125], v[142:145], v[166:169], v[122:125]
	v_mfma_f32_16x16x32_bf16 v[118:121], v[134:137], v[186:189], v[118:121]
	v_mfma_f32_16x16x32_bf16 v[114:117], v[142:145], v[186:189], v[114:117]
	v_mfma_f32_16x16x32_bf16 v[110:113], v[134:137], v[196:199], v[110:113]
	v_mfma_f32_16x16x32_bf16 v[106:109], v[142:145], v[196:199], v[106:109]
	v_mfma_f32_16x16x32_bf16 v[102:105], v[134:137], v[214:217], v[102:105]
	v_mfma_f32_16x16x32_bf16 v[98:101], v[142:145], v[214:217], v[98:101]
	s_setprio 0
	s_setprio 1
	v_mfma_f32_16x16x32_bf16 v[82:85], v[146:149], v[162:165], v[82:85]
	v_mfma_f32_16x16x32_bf16 v[74:77], v[154:157], v[162:165], v[74:77]
	v_mfma_f32_16x16x32_bf16 v[70:73], v[146:149], v[170:173], v[70:73]
	v_mfma_f32_16x16x32_bf16 v[62:65], v[154:157], v[170:173], v[62:65]
	v_mfma_f32_16x16x32_bf16 v[54:57], v[146:149], v[192:195], v[54:57]
	v_mfma_f32_16x16x32_bf16 v[50:53], v[154:157], v[192:195], v[50:53]
	v_mfma_f32_16x16x32_bf16 v[38:41], v[146:149], v[210:213], v[38:41]
	v_mfma_f32_16x16x32_bf16 v[34:37], v[154:157], v[210:213], v[34:37]
	v_mfma_f32_16x16x32_bf16 v[82:85], v[150:153], v[166:169], v[82:85]
	v_mfma_f32_16x16x32_bf16 v[74:77], v[158:161], v[166:169], v[74:77]
	v_mfma_f32_16x16x32_bf16 v[70:73], v[150:153], v[186:189], v[70:73]
	v_mfma_f32_16x16x32_bf16 v[62:65], v[158:161], v[186:189], v[62:65]
	v_mfma_f32_16x16x32_bf16 v[54:57], v[150:153], v[196:199], v[54:57]
	v_mfma_f32_16x16x32_bf16 v[50:53], v[158:161], v[196:199], v[50:53]
	v_mfma_f32_16x16x32_bf16 v[38:41], v[150:153], v[214:217], v[38:41]
	v_mfma_f32_16x16x32_bf16 v[34:37], v[158:161], v[214:217], v[34:37]
	s_setprio 2
	s_barrier
	s_add_i32 s72, s45, 0x10000
	s_mov_b32 m0, s72
	ds_read_b128 v[162:165], v209 offset:16384
	ds_read_b128 v[166:169], v209 offset:17408
	ds_read_b128 v[170:173], v209 offset:18432
	ds_read_b128 v[186:189], v209 offset:19456
	ds_read_b128 v[192:195], v209 offset:20480
	ds_read_b128 v[196:199], v209 offset:21504
	ds_read_b128 v[210:213], v209 offset:22528
	ds_read_b128 v[214:217], v209 offset:23552
	global_load_lds_dwordx4 v0, s[70:71]
	s_add_i32 m0, s72, 0x2000
	s_add_i32 s72, s45, 0x14000
	global_load_lds_dwordx4 v174, s[70:71]
	s_add_u32 s70, s70, s84
	s_addc_u32 s71, s71, 0
	s_mov_b32 m0, s72
	s_nop 0
	global_load_lds_dwordx4 v0, s[70:71]
	s_add_i32 m0, s72, 0x2000
	s_nop 0
	global_load_lds_dwordx4 v174, s[70:71]
	s_mov_b32 m0, s23
	s_nop 0
	global_load_lds_dwordx4 v178, s[38:39]
	s_waitcnt vmcnt(7)
	s_waitcnt lgkmcnt(0)
	s_barrier
	s_setprio 1
	s_waitcnt lgkmcnt(0)
	v_mfma_f32_16x16x32_bf16 v[94:97], v[130:133], v[162:165], v[94:97]
	v_mfma_f32_16x16x32_bf16 v[90:93], v[138:141], v[162:165], v[90:93]
	v_mfma_f32_16x16x32_bf16 v[86:89], v[130:133], v[170:173], v[86:89]
	v_mfma_f32_16x16x32_bf16 v[78:81], v[138:141], v[170:173], v[78:81]
	v_mfma_f32_16x16x32_bf16 v[66:69], v[130:133], v[192:195], v[66:69]
	v_mfma_f32_16x16x32_bf16 v[58:61], v[138:141], v[192:195], v[58:61]
	v_mfma_f32_16x16x32_bf16 v[46:49], v[130:133], v[210:213], v[46:49]
	v_mfma_f32_16x16x32_bf16 v[42:45], v[138:141], v[210:213], v[42:45]
	v_mfma_f32_16x16x32_bf16 v[94:97], v[134:137], v[166:169], v[94:97]
	v_mfma_f32_16x16x32_bf16 v[90:93], v[142:145], v[166:169], v[90:93]
	v_mfma_f32_16x16x32_bf16 v[86:89], v[134:137], v[186:189], v[86:89]
	v_mfma_f32_16x16x32_bf16 v[78:81], v[142:145], v[186:189], v[78:81]
	v_mfma_f32_16x16x32_bf16 v[66:69], v[134:137], v[196:199], v[66:69]
	v_mfma_f32_16x16x32_bf16 v[58:61], v[142:145], v[196:199], v[58:61]
	v_mfma_f32_16x16x32_bf16 v[46:49], v[134:137], v[214:217], v[46:49]
	v_mfma_f32_16x16x32_bf16 v[42:45], v[142:145], v[214:217], v[42:45]
	s_setprio 0
	s_setprio 1
	v_mfma_f32_16x16x32_bf16 v[30:33], v[146:149], v[162:165], v[30:33]
	v_mfma_f32_16x16x32_bf16 v[26:29], v[154:157], v[162:165], v[26:29]
	v_mfma_f32_16x16x32_bf16 v[22:25], v[146:149], v[170:173], v[22:25]
	v_mfma_f32_16x16x32_bf16 v[18:21], v[154:157], v[170:173], v[18:21]
	v_mfma_f32_16x16x32_bf16 v[14:17], v[146:149], v[192:195], v[14:17]
	v_mfma_f32_16x16x32_bf16 v[10:13], v[154:157], v[192:195], v[10:13]
	v_mfma_f32_16x16x32_bf16 v[6:9], v[146:149], v[210:213], v[6:9]
	v_mfma_f32_16x16x32_bf16 v[2:5], v[154:157], v[210:213], v[2:5]
	v_mfma_f32_16x16x32_bf16 v[30:33], v[150:153], v[166:169], v[30:33]
	v_mfma_f32_16x16x32_bf16 v[26:29], v[158:161], v[166:169], v[26:29]
	v_mfma_f32_16x16x32_bf16 v[22:25], v[150:153], v[186:189], v[22:25]
	v_mfma_f32_16x16x32_bf16 v[18:21], v[158:161], v[186:189], v[18:21]
	v_mfma_f32_16x16x32_bf16 v[14:17], v[150:153], v[196:199], v[14:17]
	v_mfma_f32_16x16x32_bf16 v[10:13], v[158:161], v[196:199], v[10:13]
	v_mfma_f32_16x16x32_bf16 v[6:9], v[150:153], v[214:217], v[6:9]
	v_mfma_f32_16x16x32_bf16 v[2:5], v[158:161], v[214:217], v[2:5]
	s_setprio 2
	s_barrier
	s_mov_b32 m0, s51
	ds_read_b128 v[130:133], v202 offset:32768
	ds_read_b128 v[134:137], v202 offset:33792
	ds_read_b128 v[138:141], v202 offset:34816
	ds_read_b128 v[142:145], v202 offset:35840
	ds_read_b128 v[146:149], v202 offset:49152
	ds_read_b128 v[150:153], v202 offset:50176
	ds_read_b128 v[154:157], v202 offset:51200
	ds_read_b128 v[158:161], v202 offset:52224
	ds_read_b128 v[162:165], v209 offset:32768
	ds_read_b128 v[166:169], v209 offset:33792
	ds_read_b128 v[170:173], v209 offset:34816
	ds_read_b128 v[186:189], v209 offset:35840
	ds_read_b128 v[192:195], v209 offset:36864
	ds_read_b128 v[196:199], v209 offset:37888
	ds_read_b128 v[210:213], v209 offset:38912
	ds_read_b128 v[214:217], v209 offset:39936
	global_load_lds_dwordx4 v176, s[38:39]
	s_add_u32 s38, s38, s84
	s_addc_u32 s39, s39, 0
	s_mov_b32 m0, s52
	s_nop 0
	global_load_lds_dwordx4 v178, s[38:39]
	s_mov_b32 m0, s53
	s_nop 0
	global_load_lds_dwordx4 v176, s[38:39]
	s_waitcnt vmcnt(8)
	s_waitcnt lgkmcnt(0)
	s_barrier
	s_setprio 1
	s_waitcnt lgkmcnt(0)
	v_mfma_f32_16x16x32_bf16 v[126:129], v[130:133], v[162:165], v[126:129]
	v_mfma_f32_16x16x32_bf16 v[122:125], v[138:141], v[162:165], v[122:125]
	v_mfma_f32_16x16x32_bf16 v[118:121], v[130:133], v[170:173], v[118:121]
	v_mfma_f32_16x16x32_bf16 v[114:117], v[138:141], v[170:173], v[114:117]
	v_mfma_f32_16x16x32_bf16 v[110:113], v[130:133], v[192:195], v[110:113]
	v_mfma_f32_16x16x32_bf16 v[106:109], v[138:141], v[192:195], v[106:109]
	v_mfma_f32_16x16x32_bf16 v[102:105], v[130:133], v[210:213], v[102:105]
	v_mfma_f32_16x16x32_bf16 v[98:101], v[138:141], v[210:213], v[98:101]
	v_mfma_f32_16x16x32_bf16 v[126:129], v[134:137], v[166:169], v[126:129]
	v_mfma_f32_16x16x32_bf16 v[122:125], v[142:145], v[166:169], v[122:125]
	v_mfma_f32_16x16x32_bf16 v[118:121], v[134:137], v[186:189], v[118:121]
	v_mfma_f32_16x16x32_bf16 v[114:117], v[142:145], v[186:189], v[114:117]
	v_mfma_f32_16x16x32_bf16 v[110:113], v[134:137], v[196:199], v[110:113]
	v_mfma_f32_16x16x32_bf16 v[106:109], v[142:145], v[196:199], v[106:109]
	v_mfma_f32_16x16x32_bf16 v[102:105], v[134:137], v[214:217], v[102:105]
	v_mfma_f32_16x16x32_bf16 v[98:101], v[142:145], v[214:217], v[98:101]
	s_setprio 0
	s_setprio 1
	v_mfma_f32_16x16x32_bf16 v[82:85], v[146:149], v[162:165], v[82:85]
	v_mfma_f32_16x16x32_bf16 v[74:77], v[154:157], v[162:165], v[74:77]
	v_mfma_f32_16x16x32_bf16 v[70:73], v[146:149], v[170:173], v[70:73]
	v_mfma_f32_16x16x32_bf16 v[62:65], v[154:157], v[170:173], v[62:65]
	v_mfma_f32_16x16x32_bf16 v[54:57], v[146:149], v[192:195], v[54:57]
	v_mfma_f32_16x16x32_bf16 v[50:53], v[154:157], v[192:195], v[50:53]
	v_mfma_f32_16x16x32_bf16 v[38:41], v[146:149], v[210:213], v[38:41]
	v_mfma_f32_16x16x32_bf16 v[34:37], v[154:157], v[210:213], v[34:37]
	v_mfma_f32_16x16x32_bf16 v[82:85], v[150:153], v[166:169], v[82:85]
	v_mfma_f32_16x16x32_bf16 v[74:77], v[158:161], v[166:169], v[74:77]
	v_mfma_f32_16x16x32_bf16 v[70:73], v[150:153], v[186:189], v[70:73]
	v_mfma_f32_16x16x32_bf16 v[62:65], v[158:161], v[186:189], v[62:65]
	v_mfma_f32_16x16x32_bf16 v[54:57], v[150:153], v[196:199], v[54:57]
	v_mfma_f32_16x16x32_bf16 v[50:53], v[158:161], v[196:199], v[50:53]
	v_mfma_f32_16x16x32_bf16 v[38:41], v[150:153], v[214:217], v[38:41]
	v_mfma_f32_16x16x32_bf16 v[34:37], v[158:161], v[214:217], v[34:37]
	s_setprio 2
	s_barrier
	s_add_u32 s70, s70, 0x80
	s_addc_u32 s71, s71, 0
	s_add_i32 s72, s45, 0x1c000
	s_mov_b32 m0, s72
	ds_read_b128 v[162:165], v209 offset:49152
	ds_read_b128 v[166:169], v209 offset:50176
	ds_read_b128 v[170:173], v209 offset:51200
	ds_read_b128 v[186:189], v209 offset:52224
	ds_read_b128 v[192:195], v209 offset:53248
	ds_read_b128 v[196:199], v209 offset:54272
	ds_read_b128 v[210:213], v209 offset:55296
	ds_read_b128 v[214:217], v209 offset:56320
	global_load_lds_dwordx4 v0, s[70:71]
	s_add_i32 m0, s72, 0x2000
	s_add_i32 s72, s45, 0x18000
	global_load_lds_dwordx4 v174, s[70:71]
	s_sub_u32 s70, s70, s84
	s_subb_u32 s71, s71, 0
	s_mov_b32 m0, s72
	s_sub_u32 s38, s38, s84
	global_load_lds_dwordx4 v0, s[70:71]
	s_subb_u32 s39, s39, 0
	s_add_i32 m0, s72, 0x2000
	s_add_u32 s38, s38, 0x80
	global_load_lds_dwordx4 v174, s[70:71]
	s_addc_u32 s39, s39, 0
	s_mov_b32 m0, s54
	s_nop 0
	global_load_lds_dwordx4 v178, s[38:39]
	s_waitcnt vmcnt(7)
	s_waitcnt lgkmcnt(0)
	s_barrier
	s_setprio 1
	s_waitcnt lgkmcnt(0)
	v_mfma_f32_16x16x32_bf16 v[94:97], v[130:133], v[162:165], v[94:97]
	v_mfma_f32_16x16x32_bf16 v[90:93], v[138:141], v[162:165], v[90:93]
	v_mfma_f32_16x16x32_bf16 v[86:89], v[130:133], v[170:173], v[86:89]
	v_mfma_f32_16x16x32_bf16 v[78:81], v[138:141], v[170:173], v[78:81]
	v_mfma_f32_16x16x32_bf16 v[66:69], v[130:133], v[192:195], v[66:69]
	v_mfma_f32_16x16x32_bf16 v[58:61], v[138:141], v[192:195], v[58:61]
	v_mfma_f32_16x16x32_bf16 v[46:49], v[130:133], v[210:213], v[46:49]
	v_mfma_f32_16x16x32_bf16 v[42:45], v[138:141], v[210:213], v[42:45]
	v_mfma_f32_16x16x32_bf16 v[94:97], v[134:137], v[166:169], v[94:97]
	v_mfma_f32_16x16x32_bf16 v[90:93], v[142:145], v[166:169], v[90:93]
	v_mfma_f32_16x16x32_bf16 v[86:89], v[134:137], v[186:189], v[86:89]
	v_mfma_f32_16x16x32_bf16 v[78:81], v[142:145], v[186:189], v[78:81]
	v_mfma_f32_16x16x32_bf16 v[66:69], v[134:137], v[196:199], v[66:69]
	v_mfma_f32_16x16x32_bf16 v[58:61], v[142:145], v[196:199], v[58:61]
	v_mfma_f32_16x16x32_bf16 v[46:49], v[134:137], v[214:217], v[46:49]
	v_mfma_f32_16x16x32_bf16 v[42:45], v[142:145], v[214:217], v[42:45]
	s_setprio 0
	s_setprio 1
	v_mfma_f32_16x16x32_bf16 v[30:33], v[146:149], v[162:165], v[30:33]
	v_mfma_f32_16x16x32_bf16 v[26:29], v[154:157], v[162:165], v[26:29]
	v_mfma_f32_16x16x32_bf16 v[22:25], v[146:149], v[170:173], v[22:25]
	v_mfma_f32_16x16x32_bf16 v[18:21], v[154:157], v[170:173], v[18:21]
	v_mfma_f32_16x16x32_bf16 v[14:17], v[146:149], v[192:195], v[14:17]
	v_mfma_f32_16x16x32_bf16 v[10:13], v[154:157], v[192:195], v[10:13]
	v_mfma_f32_16x16x32_bf16 v[6:9], v[146:149], v[210:213], v[6:9]
	v_mfma_f32_16x16x32_bf16 v[2:5], v[154:157], v[210:213], v[2:5]
	v_mfma_f32_16x16x32_bf16 v[30:33], v[150:153], v[166:169], v[30:33]
	v_mfma_f32_16x16x32_bf16 v[26:29], v[158:161], v[166:169], v[26:29]
	v_mfma_f32_16x16x32_bf16 v[22:25], v[150:153], v[186:189], v[22:25]
	v_mfma_f32_16x16x32_bf16 v[18:21], v[158:161], v[186:189], v[18:21]
	v_mfma_f32_16x16x32_bf16 v[14:17], v[150:153], v[196:199], v[14:17]
	v_mfma_f32_16x16x32_bf16 v[10:13], v[158:161], v[196:199], v[10:13]
	v_mfma_f32_16x16x32_bf16 v[6:9], v[150:153], v[214:217], v[6:9]
	v_mfma_f32_16x16x32_bf16 v[2:5], v[158:161], v[214:217], v[2:5]
	s_setprio 2
	s_barrier
	s_add_u32 s36, s36, 0x100
	s_addc_u32 s37, s37, 0
	s_add_u32 s67, s67, 0x100
	s_addc_u32 s68, s68, 0
	s_cmp_ge_u32 s69, s59
	s_mov_b32 s38, s69
	s_cbranch_scc0 .LBB0_458
	s_and_b64 vcc, exec, s[18:19]
	s_cbranch_vccz .LBB0_461
	s_barrier
